# barriers 1-5 rewritten: per-XCD leader election, one cross-XCD arrival counter, last leader releases all XCD generation words with one 16-lane add, buffer_inv issued before polling; barrier 0 keeps th
# speedup vs baseline: 1.0092x; 1.0024x over previous
; __device__ __forceinline__ unsigned xb_ld(unsigned* p)              { return __hip_atomic_load(p, __ATOMIC_RELAXED, __HIP_MEMORY_SCOPE_AGENT); }
; __device__ __forceinline__ unsigned xb_add(unsigned* p, unsigned v) { return __hip_atomic_fetch_add(p, v, __ATOMIC_RELAXED, __HIP_MEMORY_SCOPE_AGENT); }
; #define XB_SPIN(cond, bar) do { unsigned _sp = 0; while (cond) { __builtin_amdgcn_s_sleep(1); \
;     if ((++_sp & 255u) == 0u) { if (xb_ld(&(bar)[XB_TMO])) break; if (_sp > XB_SPIN_CAP) { atomicAdd(&(bar)[XB_TMO], 1u); break; } } } } while (0)
; __device__ __forceinline__ void xcd_barrier(const XcdBarrier& b) {
;     asm volatile("s_waitcnt vmcnt(0)" ::: "memory");
;     __syncthreads();
;     if (threadIdx.x == 0) {
;         unsigned* bar = b.bar;
;         __builtin_amdgcn_s_waitcnt(0);
;         unsigned nloc = b.st[0], nx = b.st[1];
;         if (nloc == 0u) { xcd_barrier_complete(bar, b.x, nloc, nx); b.st[0] = nloc; b.st[1] = nx; }
;         const unsigned old = xb_add(&bar[XB_XSUB(b.x)], 1u);
;         const unsigned gen = old / nloc;
;         if (old + 1u == (gen + 1u) * nloc) {
;             __builtin_amdgcn_fence(__ATOMIC_RELEASE, "agent");
;             asm volatile("s_waitcnt vmcnt(0)" ::: "memory");
;             const unsigned og = xb_add(&bar[XB_TOP], 1u);
;             const unsigned tg = og / nx;
;             if (og + 1u == (tg + 1u) * nx) xb_add(&bar[XB_TOPGEN], 1u);
;             else XB_SPIN(xb_ld(&bar[XB_TOPGEN]) == tg, bar);
;             __builtin_amdgcn_fence(__ATOMIC_ACQUIRE, "agent");
;             xb_add(&bar[XB_XGEN(b.x)], 1u);
;             asm volatile("s_waitcnt vmcnt(0)" ::: "memory");
;         } else {
;             XB_SPIN(xb_ld(&bar[XB_XGEN(b.x)]) == gen, bar);
;             __builtin_amdgcn_fence(__ATOMIC_ACQUIRE, "agent");
;             asm volatile("s_waitcnt vmcnt(0)" ::: "memory");
;         }
.LBB0_157:
	s_cmp_gt_i32 s75, 2
	s_cselect_b64 s[0:1], -1, 0
	s_and_b64 s[2:3], s[4:5], s[0:1]
	s_andn2_b64 vcc, exec, s[2:3]
	s_cbranch_vccnz .LBB0_211
	s_waitcnt vmcnt(0)
	s_waitcnt vmcnt(0) lgkmcnt(0)
	s_barrier
	s_mov_b64 s[2:3], exec
	v_readlane_b32 s4, v254, 9
	v_readlane_b32 s5, v254, 10
	s_and_b64 s[4:5], s[2:3], s[4:5]
	s_mov_b64 exec, s[4:5]
	s_cbranch_execz .LBB0_210
	s_cmp_eq_u32 s74, 1
	s_cbranch_scc1 .Lmy_fb_1_orig
	s_add_i32 s4, 0, 0x26700
	v_mov_b32_e32 v0, s4
	ds_read2_b32 v[2:3], v0 offset1:1
	s_lshl_b32 s4, s88, 8
	s_add_u32 s4, s72, s4
	s_addc_u32 s5, s73, 0
	v_mov_b32_e32 v4, 0x1000
	v_mov_b32_e32 v5, 1
	global_atomic_add v4, v4, v5, s[4:5] offset:1024 sc0
	s_sub_i32 s6, 2, s74
	s_waitcnt lgkmcnt(0)
	v_readfirstlane_b32 s7, v2
	v_readfirstlane_b32 s8, v3
	s_mul_i32 s7, s7, s6
	s_mul_i32 s8, s8, s6
	v_mov_b32_e32 v6, 0x2000
	s_waitcnt vmcnt(0)
	v_readfirstlane_b32 s10, v4
	s_add_i32 s10, s10, 1
	s_cmp_lg_u32 s10, s7
	s_cbranch_scc1 .Lmy_fb_1_wait
	buffer_wbl2 sc1
	v_mov_b32_e32 v4, 0x3000
	s_waitcnt vmcnt(0)
	global_atomic_add v4, v4, v5, s[72:73] offset:1024 sc0
	s_waitcnt vmcnt(0)
	v_readfirstlane_b32 s10, v4
	s_add_i32 s10, s10, 1
	s_cmp_lg_u32 s10, s8
	s_cbranch_scc1 .Lmy_fb_1_wait
	s_mov_b64 s[10:11], exec
	s_mov_b64 exec, 0xffff
	v_mbcnt_lo_u32_b32 v7, -1, 0
	v_lshlrev_b32_e32 v7, 8, v7
	v_add_u32_e32 v7, 0x2400, v7
	v_mov_b32_e32 v8, 1
	global_atomic_add v7, v8, s[72:73]
	s_mov_b64 exec, s[10:11]
.Lmy_fb_1_wait:
	buffer_inv sc1
	s_mov_b32 s11, 0
.Lmy_fb_1_spin:
	global_load_dword v0, v6, s[4:5] offset:1024 sc1
	s_waitcnt vmcnt(0)
	v_readfirstlane_b32 s10, v0
	s_cmp_ge_u32 s10, s6
	s_cbranch_scc1 .LBB0_210
	s_sleep 2
	s_add_i32 s11, s11, 1
	s_cmp_lt_u32 s11, 0x40000
	s_cbranch_scc1 .Lmy_fb_1_spin
	s_branch .LBB0_210
.Lmy_fb_1_orig:
	s_add_i32 s4, 0, 0x26700
	v_mov_b32_e32 v0, s4
	s_waitcnt vmcnt(0) expcnt(0) lgkmcnt(0)
	ds_read_b32 v2, v0
	s_add_i32 s4, 0, 0x26704
	v_mov_b32_e32 v0, s4
	ds_read_b32 v0, v0
	s_waitcnt lgkmcnt(1)
	v_cmp_ne_u32_e32 vcc, 0, v2
	s_cbranch_vccnz .LBB0_174
	v_readlane_b32 s4, v254, 8
	s_mul_i32 s18, s85, s4
	s_add_u32 s4, s72, 0x1000
	s_addc_u32 s5, s73, 0
	s_add_u32 s6, s72, 0x1100
	s_addc_u32 s7, s73, 0
	s_add_u32 s8, s72, 0x1200
	s_addc_u32 s9, s73, 0
	s_add_u32 s10, s72, 0x1300
	s_mul_i32 s18, s18, s84
	s_addc_u32 s11, s73, 0
	s_mov_b32 s19, 1
	v_mov_b32_e32 v16, 0
	s_branch .LBB0_162

; __device__ __forceinline__ unsigned xb_ld(unsigned* p)              { return __hip_atomic_load(p, __ATOMIC_RELAXED, __HIP_MEMORY_SCOPE_AGENT); }
; __device__ __forceinline__ unsigned xb_add(unsigned* p, unsigned v) { return __hip_atomic_fetch_add(p, v, __ATOMIC_RELAXED, __HIP_MEMORY_SCOPE_AGENT); }
; #define XB_SPIN(cond, bar) do { unsigned _sp = 0; while (cond) { __builtin_amdgcn_s_sleep(1); \
;     if ((++_sp & 255u) == 0u) { if (xb_ld(&(bar)[XB_TMO])) break; if (_sp > XB_SPIN_CAP) { atomicAdd(&(bar)[XB_TMO], 1u); break; } } } } while (0)
; __device__ __forceinline__ void xcd_barrier(const XcdBarrier& b) {
;     asm volatile("s_waitcnt vmcnt(0)" ::: "memory");
;     __syncthreads();
;     if (threadIdx.x == 0) {
;         unsigned* bar = b.bar;
;         __builtin_amdgcn_s_waitcnt(0);
;         unsigned nloc = b.st[0], nx = b.st[1];
;         if (nloc == 0u) { xcd_barrier_complete(bar, b.x, nloc, nx); b.st[0] = nloc; b.st[1] = nx; }
;         const unsigned old = xb_add(&bar[XB_XSUB(b.x)], 1u);
;         const unsigned gen = old / nloc;
;         if (old + 1u == (gen + 1u) * nloc) {
;             __builtin_amdgcn_fence(__ATOMIC_RELEASE, "agent");
;             asm volatile("s_waitcnt vmcnt(0)" ::: "memory");
;             const unsigned og = xb_add(&bar[XB_TOP], 1u);
;             const unsigned tg = og / nx;
;             if (og + 1u == (tg + 1u) * nx) xb_add(&bar[XB_TOPGEN], 1u);
;             else XB_SPIN(xb_ld(&bar[XB_TOPGEN]) == tg, bar);
;             __builtin_amdgcn_fence(__ATOMIC_ACQUIRE, "agent");
;             xb_add(&bar[XB_XGEN(b.x)], 1u);
;             asm volatile("s_waitcnt vmcnt(0)" ::: "memory");
;         } else {
;             XB_SPIN(xb_ld(&bar[XB_XGEN(b.x)]) == gen, bar);
;             __builtin_amdgcn_fence(__ATOMIC_ACQUIRE, "agent");
;             asm volatile("s_waitcnt vmcnt(0)" ::: "memory");
;         }
.LBB0_723:
	s_cmp_gt_i32 s75, 3
	s_cselect_b64 s[0:1], -1, 0
	s_and_b64 s[2:3], s[2:3], s[0:1]
	s_andn2_b64 vcc, exec, s[2:3]
	s_cbranch_vccnz .LBB0_777
	s_waitcnt vmcnt(0)
	s_waitcnt vmcnt(0) lgkmcnt(0)
	s_barrier
	s_mov_b64 s[2:3], exec
	v_readlane_b32 s4, v254, 9
	v_readlane_b32 s5, v254, 10
	s_and_b64 s[4:5], s[2:3], s[4:5]
	s_mov_b64 exec, s[4:5]
	s_cbranch_execz .LBB0_776
	s_cmp_eq_u32 s74, 2
	s_cbranch_scc1 .Lmy_fb_2_orig
	s_add_i32 s4, 0, 0x26700
	v_mov_b32_e32 v0, s4
	ds_read2_b32 v[2:3], v0 offset1:1
	s_lshl_b32 s4, s88, 8
	s_add_u32 s4, s72, s4
	s_addc_u32 s5, s73, 0
	v_mov_b32_e32 v4, 0x1000
	v_mov_b32_e32 v5, 1
	global_atomic_add v4, v4, v5, s[4:5] offset:1024 sc0
	s_sub_i32 s6, 3, s74
	s_waitcnt lgkmcnt(0)
	v_readfirstlane_b32 s7, v2
	v_readfirstlane_b32 s8, v3
	s_mul_i32 s7, s7, s6
	s_mul_i32 s8, s8, s6
	v_mov_b32_e32 v6, 0x2000
	s_waitcnt vmcnt(0)
	v_readfirstlane_b32 s10, v4
	s_add_i32 s10, s10, 1
	s_cmp_lg_u32 s10, s7
	s_cbranch_scc1 .Lmy_fb_2_wait
	buffer_wbl2 sc1
	v_mov_b32_e32 v4, 0x3000
	s_waitcnt vmcnt(0)
	global_atomic_add v4, v4, v5, s[72:73] offset:1024 sc0
	s_waitcnt vmcnt(0)
	v_readfirstlane_b32 s10, v4
	s_add_i32 s10, s10, 1
	s_cmp_lg_u32 s10, s8
	s_cbranch_scc1 .Lmy_fb_2_wait
	s_mov_b64 s[10:11], exec
	s_mov_b64 exec, 0xffff
	v_mbcnt_lo_u32_b32 v7, -1, 0
	v_lshlrev_b32_e32 v7, 8, v7
	v_add_u32_e32 v7, 0x2400, v7
	v_mov_b32_e32 v8, 1
	global_atomic_add v7, v8, s[72:73]
	s_mov_b64 exec, s[10:11]

; __device__ __forceinline__ unsigned xb_ld(unsigned* p)              { return __hip_atomic_load(p, __ATOMIC_RELAXED, __HIP_MEMORY_SCOPE_AGENT); }
; __device__ __forceinline__ unsigned xb_add(unsigned* p, unsigned v) { return __hip_atomic_fetch_add(p, v, __ATOMIC_RELAXED, __HIP_MEMORY_SCOPE_AGENT); }
; #define XB_SPIN(cond, bar) do { unsigned _sp = 0; while (cond) { __builtin_amdgcn_s_sleep(1); \
;     if ((++_sp & 255u) == 0u) { if (xb_ld(&(bar)[XB_TMO])) break; if (_sp > XB_SPIN_CAP) { atomicAdd(&(bar)[XB_TMO], 1u); break; } } } } while (0)
; __device__ __forceinline__ void xcd_barrier(const XcdBarrier& b) {
;     asm volatile("s_waitcnt vmcnt(0)" ::: "memory");
;     __syncthreads();
;     if (threadIdx.x == 0) {
;         unsigned* bar = b.bar;
;         __builtin_amdgcn_s_waitcnt(0);
;         unsigned nloc = b.st[0], nx = b.st[1];
;         if (nloc == 0u) { xcd_barrier_complete(bar, b.x, nloc, nx); b.st[0] = nloc; b.st[1] = nx; }
;         const unsigned old = xb_add(&bar[XB_XSUB(b.x)], 1u);
;         const unsigned gen = old / nloc;
;         if (old + 1u == (gen + 1u) * nloc) {
;             __builtin_amdgcn_fence(__ATOMIC_RELEASE, "agent");
;             asm volatile("s_waitcnt vmcnt(0)" ::: "memory");
;             const unsigned og = xb_add(&bar[XB_TOP], 1u);
;             const unsigned tg = og / nx;
;             if (og + 1u == (tg + 1u) * nx) xb_add(&bar[XB_TOPGEN], 1u);
;             else XB_SPIN(xb_ld(&bar[XB_TOPGEN]) == tg, bar);
;             __builtin_amdgcn_fence(__ATOMIC_ACQUIRE, "agent");
;             xb_add(&bar[XB_XGEN(b.x)], 1u);
;             asm volatile("s_waitcnt vmcnt(0)" ::: "memory");
;         } else {
;             XB_SPIN(xb_ld(&bar[XB_XGEN(b.x)]) == gen, bar);
;             __builtin_amdgcn_fence(__ATOMIC_ACQUIRE, "agent");
;             asm volatile("s_waitcnt vmcnt(0)" ::: "memory");
;         }
.LBB0_808:
	s_cmp_gt_i32 s75, 4
	s_cselect_b64 s[2:3], -1, 0
	s_and_b64 s[0:1], s[0:1], s[2:3]
	s_andn2_b64 vcc, exec, s[0:1]
	s_cbranch_vccnz .LBB0_862
	s_waitcnt vmcnt(0)
	s_waitcnt vmcnt(0) lgkmcnt(0)
	s_barrier
	s_mov_b64 s[0:1], exec
	v_readlane_b32 s4, v254, 9
	v_readlane_b32 s5, v254, 10
	s_and_b64 s[4:5], s[0:1], s[4:5]
	s_mov_b64 exec, s[4:5]
	s_cbranch_execz .LBB0_861
	s_cmp_eq_u32 s74, 3
	s_cbranch_scc1 .Lmy_fb_3_orig
	s_add_i32 s4, 0, 0x26700
	v_mov_b32_e32 v0, s4
	ds_read2_b32 v[2:3], v0 offset1:1
	s_lshl_b32 s4, s88, 8
	s_add_u32 s4, s72, s4
	s_addc_u32 s5, s73, 0
	v_mov_b32_e32 v4, 0x1000
	v_mov_b32_e32 v5, 1
	global_atomic_add v4, v4, v5, s[4:5] offset:1024 sc0
	s_sub_i32 s6, 4, s74
	s_waitcnt lgkmcnt(0)
	v_readfirstlane_b32 s7, v2
	v_readfirstlane_b32 s8, v3
	s_mul_i32 s7, s7, s6
	s_mul_i32 s8, s8, s6
	v_mov_b32_e32 v6, 0x2000
	s_waitcnt vmcnt(0)
	v_readfirstlane_b32 s10, v4
	s_add_i32 s10, s10, 1
	s_cmp_lg_u32 s10, s7
	s_cbranch_scc1 .Lmy_fb_3_wait
	buffer_wbl2 sc1
	v_mov_b32_e32 v4, 0x3000
	s_waitcnt vmcnt(0)
	global_atomic_add v4, v4, v5, s[72:73] offset:1024 sc0
	s_waitcnt vmcnt(0)
	v_readfirstlane_b32 s10, v4
	s_add_i32 s10, s10, 1
	s_cmp_lg_u32 s10, s8
	s_cbranch_scc1 .Lmy_fb_3_wait
	s_mov_b64 s[10:11], exec
	s_mov_b64 exec, 0xffff
	v_mbcnt_lo_u32_b32 v7, -1, 0
	v_lshlrev_b32_e32 v7, 8, v7
	v_add_u32_e32 v7, 0x2400, v7
	v_mov_b32_e32 v8, 1
	global_atomic_add v7, v8, s[72:73]
	s_mov_b64 exec, s[10:11]

; __device__ __forceinline__ unsigned xb_ld(unsigned* p)              { return __hip_atomic_load(p, __ATOMIC_RELAXED, __HIP_MEMORY_SCOPE_AGENT); }
; __device__ __forceinline__ unsigned xb_add(unsigned* p, unsigned v) { return __hip_atomic_fetch_add(p, v, __ATOMIC_RELAXED, __HIP_MEMORY_SCOPE_AGENT); }
; #define XB_SPIN(cond, bar) do { unsigned _sp = 0; while (cond) { __builtin_amdgcn_s_sleep(1); \
;     if ((++_sp & 255u) == 0u) { if (xb_ld(&(bar)[XB_TMO])) break; if (_sp > XB_SPIN_CAP) { atomicAdd(&(bar)[XB_TMO], 1u); break; } } } } while (0)
; __device__ __forceinline__ void xcd_barrier(const XcdBarrier& b) {
;     asm volatile("s_waitcnt vmcnt(0)" ::: "memory");
;     __syncthreads();
;     if (threadIdx.x == 0) {
;         unsigned* bar = b.bar;
;         __builtin_amdgcn_s_waitcnt(0);
;         unsigned nloc = b.st[0], nx = b.st[1];
;         if (nloc == 0u) { xcd_barrier_complete(bar, b.x, nloc, nx); b.st[0] = nloc; b.st[1] = nx; }
;         const unsigned old = xb_add(&bar[XB_XSUB(b.x)], 1u);
;         const unsigned gen = old / nloc;
;         if (old + 1u == (gen + 1u) * nloc) {
;             __builtin_amdgcn_fence(__ATOMIC_RELEASE, "agent");
;             asm volatile("s_waitcnt vmcnt(0)" ::: "memory");
;             const unsigned og = xb_add(&bar[XB_TOP], 1u);
;             const unsigned tg = og / nx;
;             if (og + 1u == (tg + 1u) * nx) xb_add(&bar[XB_TOPGEN], 1u);
;             else XB_SPIN(xb_ld(&bar[XB_TOPGEN]) == tg, bar);
;             __builtin_amdgcn_fence(__ATOMIC_ACQUIRE, "agent");
;             xb_add(&bar[XB_XGEN(b.x)], 1u);
;             asm volatile("s_waitcnt vmcnt(0)" ::: "memory");
;         } else {
;             XB_SPIN(xb_ld(&bar[XB_XGEN(b.x)]) == gen, bar);
;             __builtin_amdgcn_fence(__ATOMIC_ACQUIRE, "agent");
;             asm volatile("s_waitcnt vmcnt(0)" ::: "memory");
;         }
.LBB0_905:
	s_cmp_gt_i32 s75, 5
	s_cselect_b64 s[2:3], -1, 0
	s_and_b64 s[0:1], s[0:1], s[2:3]
	s_andn2_b64 vcc, exec, s[0:1]
	s_cbranch_vccnz .LBB0_959
	s_waitcnt vmcnt(0)
	s_waitcnt vmcnt(0) lgkmcnt(0)
	s_barrier
	s_mov_b64 s[0:1], exec
	v_readlane_b32 s4, v254, 9
	v_readlane_b32 s5, v254, 10
	s_and_b64 s[4:5], s[0:1], s[4:5]
	s_mov_b64 exec, s[4:5]
	s_cbranch_execz .LBB0_958
	s_cmp_eq_u32 s74, 4
	s_cbranch_scc1 .Lmy_fb_4_orig
	s_add_i32 s4, 0, 0x26700
	v_mov_b32_e32 v0, s4
	ds_read2_b32 v[2:3], v0 offset1:1
	s_lshl_b32 s4, s88, 8
	s_add_u32 s4, s72, s4
	s_addc_u32 s5, s73, 0
	v_mov_b32_e32 v4, 0x1000
	v_mov_b32_e32 v5, 1
	global_atomic_add v4, v4, v5, s[4:5] offset:1024 sc0
	s_sub_i32 s6, 5, s74
	s_waitcnt lgkmcnt(0)
	v_readfirstlane_b32 s7, v2
	v_readfirstlane_b32 s8, v3
	s_mul_i32 s7, s7, s6
	s_mul_i32 s8, s8, s6
	v_mov_b32_e32 v6, 0x2000
	s_waitcnt vmcnt(0)
	v_readfirstlane_b32 s10, v4
	s_add_i32 s10, s10, 1
	s_cmp_lg_u32 s10, s7
	s_cbranch_scc1 .Lmy_fb_4_wait
	buffer_wbl2 sc1
	v_mov_b32_e32 v4, 0x3000
	s_waitcnt vmcnt(0)
	global_atomic_add v4, v4, v5, s[72:73] offset:1024 sc0
	s_waitcnt vmcnt(0)
	v_readfirstlane_b32 s10, v4
	s_add_i32 s10, s10, 1
	s_cmp_lg_u32 s10, s8
	s_cbranch_scc1 .Lmy_fb_4_wait
	s_mov_b64 s[10:11], exec
	s_mov_b64 exec, 0xffff
	v_mbcnt_lo_u32_b32 v7, -1, 0
	v_lshlrev_b32_e32 v7, 8, v7
	v_add_u32_e32 v7, 0x2400, v7
	v_mov_b32_e32 v8, 1
	global_atomic_add v7, v8, s[72:73]
	s_mov_b64 exec, s[10:11]

; __device__ __forceinline__ unsigned xb_ld(unsigned* p)              { return __hip_atomic_load(p, __ATOMIC_RELAXED, __HIP_MEMORY_SCOPE_AGENT); }
; __device__ __forceinline__ unsigned xb_add(unsigned* p, unsigned v) { return __hip_atomic_fetch_add(p, v, __ATOMIC_RELAXED, __HIP_MEMORY_SCOPE_AGENT); }
; #define XB_SPIN(cond, bar) do { unsigned _sp = 0; while (cond) { __builtin_amdgcn_s_sleep(1); \
;     if ((++_sp & 255u) == 0u) { if (xb_ld(&(bar)[XB_TMO])) break; if (_sp > XB_SPIN_CAP) { atomicAdd(&(bar)[XB_TMO], 1u); break; } } } } while (0)
; __device__ __forceinline__ void xcd_barrier(const XcdBarrier& b) {
;     asm volatile("s_waitcnt vmcnt(0)" ::: "memory");
;     __syncthreads();
;     if (threadIdx.x == 0) {
;         unsigned* bar = b.bar;
;         __builtin_amdgcn_s_waitcnt(0);
;         unsigned nloc = b.st[0], nx = b.st[1];
;         if (nloc == 0u) { xcd_barrier_complete(bar, b.x, nloc, nx); b.st[0] = nloc; b.st[1] = nx; }
;         const unsigned old = xb_add(&bar[XB_XSUB(b.x)], 1u);
;         const unsigned gen = old / nloc;
;         if (old + 1u == (gen + 1u) * nloc) {
;             __builtin_amdgcn_fence(__ATOMIC_RELEASE, "agent");
;             asm volatile("s_waitcnt vmcnt(0)" ::: "memory");
;             const unsigned og = xb_add(&bar[XB_TOP], 1u);
;             const unsigned tg = og / nx;
;             if (og + 1u == (tg + 1u) * nx) xb_add(&bar[XB_TOPGEN], 1u);
;             else XB_SPIN(xb_ld(&bar[XB_TOPGEN]) == tg, bar);
;             __builtin_amdgcn_fence(__ATOMIC_ACQUIRE, "agent");
;             xb_add(&bar[XB_XGEN(b.x)], 1u);
;             asm volatile("s_waitcnt vmcnt(0)" ::: "memory");
;         } else {
;             XB_SPIN(xb_ld(&bar[XB_XGEN(b.x)]) == gen, bar);
;             __builtin_amdgcn_fence(__ATOMIC_ACQUIRE, "agent");
;             asm volatile("s_waitcnt vmcnt(0)" ::: "memory");
;         }
.LBB0_976:
	s_cmp_gt_i32 s75, 6
	s_cselect_b64 s[2:3], -1, 0
	s_and_b64 s[0:1], s[0:1], s[2:3]
	s_andn2_b64 vcc, exec, s[0:1]
	s_cbranch_vccnz .LBB0_1030
	s_waitcnt vmcnt(0)
	s_waitcnt vmcnt(0) lgkmcnt(0)
	s_barrier
	s_mov_b64 s[0:1], exec
	v_readlane_b32 s4, v254, 9
	v_readlane_b32 s5, v254, 10
	s_and_b64 s[4:5], s[0:1], s[4:5]
	s_mov_b64 exec, s[4:5]
	s_cbranch_execz .LBB0_1029
	s_cmp_eq_u32 s74, 5
	s_cbranch_scc1 .Lmy_fb_5_orig
	s_add_i32 s4, 0, 0x26700
	v_mov_b32_e32 v0, s4
	ds_read2_b32 v[2:3], v0 offset1:1
	s_lshl_b32 s4, s88, 8
	s_add_u32 s4, s72, s4
	s_addc_u32 s5, s73, 0
	v_mov_b32_e32 v4, 0x1000
	v_mov_b32_e32 v5, 1
	global_atomic_add v4, v4, v5, s[4:5] offset:1024 sc0
	s_sub_i32 s6, 6, s74
	s_waitcnt lgkmcnt(0)
	v_readfirstlane_b32 s7, v2
	v_readfirstlane_b32 s8, v3
	s_mul_i32 s7, s7, s6
	s_mul_i32 s8, s8, s6
	v_mov_b32_e32 v6, 0x2000
	s_waitcnt vmcnt(0)
	v_readfirstlane_b32 s10, v4
	s_add_i32 s10, s10, 1
	s_cmp_lg_u32 s10, s7
	s_cbranch_scc1 .Lmy_fb_5_wait
	buffer_wbl2 sc1
	v_mov_b32_e32 v4, 0x3000
	s_waitcnt vmcnt(0)
	global_atomic_add v4, v4, v5, s[72:73] offset:1024 sc0
	s_waitcnt vmcnt(0)
	v_readfirstlane_b32 s10, v4
	s_add_i32 s10, s10, 1
	s_cmp_lg_u32 s10, s8
	s_cbranch_scc1 .Lmy_fb_5_wait
	s_mov_b64 s[10:11], exec
	s_mov_b64 exec, 0xffff
	v_mbcnt_lo_u32_b32 v7, -1, 0
	v_lshlrev_b32_e32 v7, 8, v7
	v_add_u32_e32 v7, 0x2400, v7
	v_mov_b32_e32 v8, 1
	global_atomic_add v7, v8, s[72:73]
	s_mov_b64 exec, s[10:11]
